# grid barrier: non-leader workgroups poll the cross-XCD release generation directly instead of the per-XCD one (one less release hop)
# speedup vs baseline: 1.0163x; 1.0163x over previous
;   DI unsigned* bar() const { return (unsigned*)(ws + OFF_BAR); }
; __device__ __forceinline__ unsigned xb_ld(unsigned* p)              { return __hip_atomic_load(p, __ATOMIC_RELAXED, __HIP_MEMORY_SCOPE_AGENT); }
; __device__ __forceinline__ unsigned xb_add(unsigned* p, unsigned v) { return __hip_atomic_fetch_add(p, v, __ATOMIC_RELAXED, __HIP_MEMORY_SCOPE_AGENT); }
; #define XB_SPIN(cond, bar) do { unsigned _sp = 0; while (cond) { __builtin_amdgcn_s_sleep(1); \
;     if ((++_sp & 255u) == 0u) { if (xb_ld(&(bar)[XB_TMO])) break; if (_sp > XB_SPIN_CAP) { atomicAdd(&(bar)[XB_TMO], 1u); break; } } } } while (0)
; __device__ __forceinline__ void xcd_barrier(const XcdBarrier& b) {
;     ...
;     if (threadIdx.x == 0) {
;         unsigned* bar = b.bar;
;         __builtin_amdgcn_s_waitcnt(0);
;         unsigned nloc = b.st[0], nx = b.st[1];
;         if (nloc == 0u) { xcd_barrier_complete(bar, b.x, nloc, nx); b.st[0] = nloc; b.st[1] = nx; }
;         const unsigned old = xb_add(&bar[XB_XSUB(b.x)], 1u);
;         const unsigned gen = old / nloc;
;         if (old + 1u == (gen + 1u) * nloc) {
;             __builtin_amdgcn_fence(__ATOMIC_RELEASE, "agent");
;             asm volatile("s_waitcnt vmcnt(0)" ::: "memory");
;             const unsigned og = xb_add(&bar[XB_TOP], 1u);
;             const unsigned tg = og / nx;
;             if (og + 1u == (tg + 1u) * nx) xb_add(&bar[XB_TOPGEN], 1u);
;             else XB_SPIN(xb_ld(&bar[XB_TOPGEN]) == tg, bar);
;             __builtin_amdgcn_fence(__ATOMIC_ACQUIRE, "agent");
;             xb_add(&bar[XB_XGEN(b.x)], 1u);
;             asm volatile("s_waitcnt vmcnt(0)" ::: "memory");
;         } else {
;             XB_SPIN(xb_ld(&bar[XB_XGEN(b.x)]) == gen, bar);
;             __builtin_amdgcn_fence(__ATOMIC_ACQUIRE, "agent");
;             asm volatile("s_waitcnt vmcnt(0)" ::: "memory");
;         }
.Lgs_151:
	s_or_b64 exec, exec, s[6:7]
	v_cvt_f32_u32_e32 v4, v2
	s_waitcnt vmcnt(0)
	v_readfirstlane_b32 s4, v3
	v_sub_u32_e32 v3, 0, v2
	v_rcp_iflag_f32_e32 v4, v4
	v_add_u32_e32 v5, s4, v0
	v_mul_f32_e32 v4, 0x4f7ffffe, v4
	v_cvt_u32_f32_e32 v4, v4
	v_mul_lo_u32 v0, v3, v4
	v_mul_hi_u32 v0, v4, v0
	v_add_u32_e32 v0, v4, v0
	v_mul_hi_u32 v0, v5, v0
	v_mul_lo_u32 v3, v0, v2
	v_sub_u32_e32 v3, v5, v3
	v_add_u32_e32 v4, 1, v0
	v_cmp_ge_u32_e32 vcc, v3, v2
	s_nop 1
	v_cndmask_b32_e32 v0, v0, v4, vcc
	v_sub_u32_e32 v4, v3, v2
	v_cndmask_b32_e32 v3, v3, v4, vcc
	v_add_u32_e32 v4, 1, v0
	v_cmp_ge_u32_e32 vcc, v3, v2
	v_add_u32_e32 v3, 1, v5
	s_nop 0
	v_cndmask_b32_e32 v0, v0, v4, vcc
	v_mul_lo_u32 v4, v2, v0
	v_add_u32_e32 v2, v4, v2
	v_cmp_ne_u32_e32 vcc, v3, v2
	s_and_saveexec_b64 s[4:5], vcc
	s_xor_b64 s[4:5], exec, s[4:5]
	s_cbranch_execz .Lgs_165
	s_waitcnt lgkmcnt(0)
	s_add_u32 s10, s22, 0x1e6c4500
	s_addc_u32 s11, s23, 0
	v_mov_b32_e32 v1, 0
	global_load_dword v1, v1, s[10:11] sc1
	s_waitcnt vmcnt(0)
	v_cmp_eq_u32_e32 vcc, v1, v0
	s_and_saveexec_b64 s[6:7], vcc
	s_cbranch_execz .Lgs_164
	s_add_u32 s8, s22, 0x1e6c1200
	s_addc_u32 s9, s23, 0
	s_mov_b32 s26, 1
	s_mov_b64 s[12:13], 0
	v_mov_b32_e32 v1, 0
	s_branch .Lgs_155

;   DI unsigned* bar() const { return (unsigned*)(ws + OFF_BAR); }
; __device__ __forceinline__ unsigned xb_ld(unsigned* p)              { return __hip_atomic_load(p, __ATOMIC_RELAXED, __HIP_MEMORY_SCOPE_AGENT); }
; __device__ __forceinline__ unsigned xb_add(unsigned* p, unsigned v) { return __hip_atomic_fetch_add(p, v, __ATOMIC_RELAXED, __HIP_MEMORY_SCOPE_AGENT); }
; #define XB_SPIN(cond, bar) do { unsigned _sp = 0; while (cond) { __builtin_amdgcn_s_sleep(1); \
;     if ((++_sp & 255u) == 0u) { if (xb_ld(&(bar)[XB_TMO])) break; if (_sp > XB_SPIN_CAP) { atomicAdd(&(bar)[XB_TMO], 1u); break; } } } } while (0)
; __device__ __forceinline__ void xcd_barrier(const XcdBarrier& b) {
;     ...
;     if (threadIdx.x == 0) {
;         unsigned* bar = b.bar;
;         __builtin_amdgcn_s_waitcnt(0);
;         unsigned nloc = b.st[0], nx = b.st[1];
;         if (nloc == 0u) { xcd_barrier_complete(bar, b.x, nloc, nx); b.st[0] = nloc; b.st[1] = nx; }
;         const unsigned old = xb_add(&bar[XB_XSUB(b.x)], 1u);
;         const unsigned gen = old / nloc;
;         if (old + 1u == (gen + 1u) * nloc) {
;             __builtin_amdgcn_fence(__ATOMIC_RELEASE, "agent");
;             asm volatile("s_waitcnt vmcnt(0)" ::: "memory");
;             const unsigned og = xb_add(&bar[XB_TOP], 1u);
;             const unsigned tg = og / nx;
;             if (og + 1u == (tg + 1u) * nx) xb_add(&bar[XB_TOPGEN], 1u);
;             else XB_SPIN(xb_ld(&bar[XB_TOPGEN]) == tg, bar);
;             __builtin_amdgcn_fence(__ATOMIC_ACQUIRE, "agent");
;             xb_add(&bar[XB_XGEN(b.x)], 1u);
;             asm volatile("s_waitcnt vmcnt(0)" ::: "memory");
;         } else {
;             XB_SPIN(xb_ld(&bar[XB_XGEN(b.x)]) == gen, bar);
;             __builtin_amdgcn_fence(__ATOMIC_ACQUIRE, "agent");
;             asm volatile("s_waitcnt vmcnt(0)" ::: "memory");
;         }
.LBB0_643:
	s_or_b64 exec, exec, s[8:9]
	v_cvt_f32_u32_e32 v4, v2
	s_waitcnt vmcnt(0)
	v_readfirstlane_b32 s4, v3
	v_sub_u32_e32 v3, 0, v2
	v_rcp_iflag_f32_e32 v4, v4
	v_add_u32_e32 v5, s4, v0
	v_mul_f32_e32 v4, 0x4f7ffffe, v4
	v_cvt_u32_f32_e32 v4, v4
	v_mul_lo_u32 v0, v3, v4
	v_mul_hi_u32 v0, v4, v0
	v_add_u32_e32 v0, v4, v0
	v_mul_hi_u32 v0, v5, v0
	v_mul_lo_u32 v3, v0, v2
	v_sub_u32_e32 v3, v5, v3
	v_add_u32_e32 v4, 1, v0
	v_cmp_ge_u32_e32 vcc, v3, v2
	s_nop 1
	v_cndmask_b32_e32 v0, v0, v4, vcc
	v_sub_u32_e32 v4, v3, v2
	v_cndmask_b32_e32 v3, v3, v4, vcc
	v_add_u32_e32 v4, 1, v0
	v_cmp_ge_u32_e32 vcc, v3, v2
	v_add_u32_e32 v3, 1, v5
	s_nop 0
	v_cndmask_b32_e32 v0, v0, v4, vcc
	v_mul_lo_u32 v4, v2, v0
	v_add_u32_e32 v2, v4, v2
	v_cmp_ne_u32_e32 vcc, v3, v2
	s_and_saveexec_b64 s[4:5], vcc
	s_xor_b64 s[4:5], exec, s[4:5]
	s_cbranch_execz .LBB0_657
	s_waitcnt lgkmcnt(0)
	s_add_u32 s12, s22, 0x1e6c4500
	s_addc_u32 s13, s23, 0
	v_mov_b32_e32 v1, 0
	global_load_dword v1, v1, s[12:13] sc1
	s_waitcnt vmcnt(0)
	v_cmp_eq_u32_e32 vcc, v1, v0
	s_and_saveexec_b64 s[8:9], vcc
	s_cbranch_execz .LBB0_656
	s_add_u32 s10, s22, 0x1e6c1200
	s_addc_u32 s11, s23, 0
	s_mov_b32 s28, 1
	s_mov_b64 s[14:15], 0
	v_mov_b32_e32 v1, 0
	s_branch .LBB0_647

;   DI unsigned* bar() const { return (unsigned*)(ws + OFF_BAR); }
; __device__ __forceinline__ unsigned xb_ld(unsigned* p)              { return __hip_atomic_load(p, __ATOMIC_RELAXED, __HIP_MEMORY_SCOPE_AGENT); }
; __device__ __forceinline__ unsigned xb_add(unsigned* p, unsigned v) { return __hip_atomic_fetch_add(p, v, __ATOMIC_RELAXED, __HIP_MEMORY_SCOPE_AGENT); }
; #define XB_SPIN(cond, bar) do { unsigned _sp = 0; while (cond) { __builtin_amdgcn_s_sleep(1); \
;     if ((++_sp & 255u) == 0u) { if (xb_ld(&(bar)[XB_TMO])) break; if (_sp > XB_SPIN_CAP) { atomicAdd(&(bar)[XB_TMO], 1u); break; } } } } while (0)
; __device__ __forceinline__ void xcd_barrier(const XcdBarrier& b) {
;     ...
;     if (threadIdx.x == 0) {
;         unsigned* bar = b.bar;
;         __builtin_amdgcn_s_waitcnt(0);
;         unsigned nloc = b.st[0], nx = b.st[1];
;         if (nloc == 0u) { xcd_barrier_complete(bar, b.x, nloc, nx); b.st[0] = nloc; b.st[1] = nx; }
;         const unsigned old = xb_add(&bar[XB_XSUB(b.x)], 1u);
;         const unsigned gen = old / nloc;
;         if (old + 1u == (gen + 1u) * nloc) {
;             __builtin_amdgcn_fence(__ATOMIC_RELEASE, "agent");
;             asm volatile("s_waitcnt vmcnt(0)" ::: "memory");
;             const unsigned og = xb_add(&bar[XB_TOP], 1u);
;             const unsigned tg = og / nx;
;             if (og + 1u == (tg + 1u) * nx) xb_add(&bar[XB_TOPGEN], 1u);
;             else XB_SPIN(xb_ld(&bar[XB_TOPGEN]) == tg, bar);
;             __builtin_amdgcn_fence(__ATOMIC_ACQUIRE, "agent");
;             xb_add(&bar[XB_XGEN(b.x)], 1u);
;             asm volatile("s_waitcnt vmcnt(0)" ::: "memory");
;         } else {
;             XB_SPIN(xb_ld(&bar[XB_XGEN(b.x)]) == gen, bar);
;             __builtin_amdgcn_fence(__ATOMIC_ACQUIRE, "agent");
;             asm volatile("s_waitcnt vmcnt(0)" ::: "memory");
;         }
.LBB0_785:
	s_or_b64 exec, exec, s[8:9]
	v_cvt_f32_u32_e32 v4, v2
	s_waitcnt vmcnt(0)
	v_readfirstlane_b32 s6, v3
	v_sub_u32_e32 v3, 0, v2
	v_rcp_iflag_f32_e32 v4, v4
	v_add_u32_e32 v5, s6, v0
	v_mul_f32_e32 v4, 0x4f7ffffe, v4
	v_cvt_u32_f32_e32 v4, v4
	v_mul_lo_u32 v0, v3, v4
	v_mul_hi_u32 v0, v4, v0
	v_add_u32_e32 v0, v4, v0
	v_mul_hi_u32 v0, v5, v0
	v_mul_lo_u32 v3, v0, v2
	v_sub_u32_e32 v3, v5, v3
	v_add_u32_e32 v4, 1, v0
	v_cmp_ge_u32_e32 vcc, v3, v2
	s_nop 1
	v_cndmask_b32_e32 v0, v0, v4, vcc
	v_sub_u32_e32 v4, v3, v2
	v_cndmask_b32_e32 v3, v3, v4, vcc
	v_add_u32_e32 v4, 1, v0
	v_cmp_ge_u32_e32 vcc, v3, v2
	v_add_u32_e32 v3, 1, v5
	s_nop 0
	v_cndmask_b32_e32 v0, v0, v4, vcc
	v_mul_lo_u32 v4, v2, v0
	v_add_u32_e32 v2, v4, v2
	v_cmp_ne_u32_e32 vcc, v3, v2
	s_and_saveexec_b64 s[6:7], vcc
	s_xor_b64 s[6:7], exec, s[6:7]
	s_cbranch_execz .LBB0_799
	s_waitcnt lgkmcnt(0)
	s_add_u32 s12, s22, 0x1e6c4500
	s_addc_u32 s13, s23, 0
	v_mov_b32_e32 v1, 0
	global_load_dword v1, v1, s[12:13] sc1
	s_waitcnt vmcnt(0)
	v_cmp_eq_u32_e32 vcc, v1, v0
	s_and_saveexec_b64 s[8:9], vcc
	s_cbranch_execz .LBB0_798
	s_add_u32 s10, s22, 0x1e6c1200
	s_addc_u32 s11, s23, 0
	s_mov_b32 s28, 1
	s_mov_b64 s[14:15], 0
	v_mov_b32_e32 v1, 0
	s_branch .LBB0_789

;   DI unsigned* bar() const { return (unsigned*)(ws + OFF_BAR); }
; __device__ __forceinline__ unsigned xb_ld(unsigned* p)              { return __hip_atomic_load(p, __ATOMIC_RELAXED, __HIP_MEMORY_SCOPE_AGENT); }
; __device__ __forceinline__ unsigned xb_add(unsigned* p, unsigned v) { return __hip_atomic_fetch_add(p, v, __ATOMIC_RELAXED, __HIP_MEMORY_SCOPE_AGENT); }
; #define XB_SPIN(cond, bar) do { unsigned _sp = 0; while (cond) { __builtin_amdgcn_s_sleep(1); \
;     if ((++_sp & 255u) == 0u) { if (xb_ld(&(bar)[XB_TMO])) break; if (_sp > XB_SPIN_CAP) { atomicAdd(&(bar)[XB_TMO], 1u); break; } } } } while (0)
; __device__ __forceinline__ void xcd_barrier(const XcdBarrier& b) {
;     ...
;     if (threadIdx.x == 0) {
;         unsigned* bar = b.bar;
;         __builtin_amdgcn_s_waitcnt(0);
;         unsigned nloc = b.st[0], nx = b.st[1];
;         if (nloc == 0u) { xcd_barrier_complete(bar, b.x, nloc, nx); b.st[0] = nloc; b.st[1] = nx; }
;         const unsigned old = xb_add(&bar[XB_XSUB(b.x)], 1u);
;         const unsigned gen = old / nloc;
;         if (old + 1u == (gen + 1u) * nloc) {
;             __builtin_amdgcn_fence(__ATOMIC_RELEASE, "agent");
;             asm volatile("s_waitcnt vmcnt(0)" ::: "memory");
;             const unsigned og = xb_add(&bar[XB_TOP], 1u);
;             const unsigned tg = og / nx;
;             if (og + 1u == (tg + 1u) * nx) xb_add(&bar[XB_TOPGEN], 1u);
;             else XB_SPIN(xb_ld(&bar[XB_TOPGEN]) == tg, bar);
;             __builtin_amdgcn_fence(__ATOMIC_ACQUIRE, "agent");
;             xb_add(&bar[XB_XGEN(b.x)], 1u);
;             asm volatile("s_waitcnt vmcnt(0)" ::: "memory");
;         } else {
;             XB_SPIN(xb_ld(&bar[XB_XGEN(b.x)]) == gen, bar);
;             __builtin_amdgcn_fence(__ATOMIC_ACQUIRE, "agent");
;             asm volatile("s_waitcnt vmcnt(0)" ::: "memory");
;         }
.LBB0_840:
	s_or_b64 exec, exec, s[8:9]
	v_cvt_f32_u32_e32 v4, v2
	s_waitcnt vmcnt(0)
	v_readfirstlane_b32 s6, v3
	v_sub_u32_e32 v3, 0, v2
	v_rcp_iflag_f32_e32 v4, v4
	v_add_u32_e32 v5, s6, v0
	v_mul_f32_e32 v4, 0x4f7ffffe, v4
	v_cvt_u32_f32_e32 v4, v4
	v_mul_lo_u32 v0, v3, v4
	v_mul_hi_u32 v0, v4, v0
	v_add_u32_e32 v0, v4, v0
	v_mul_hi_u32 v0, v5, v0
	v_mul_lo_u32 v3, v0, v2
	v_sub_u32_e32 v3, v5, v3
	v_add_u32_e32 v4, 1, v0
	v_cmp_ge_u32_e32 vcc, v3, v2
	s_nop 1
	v_cndmask_b32_e32 v0, v0, v4, vcc
	v_sub_u32_e32 v4, v3, v2
	v_cndmask_b32_e32 v3, v3, v4, vcc
	v_add_u32_e32 v4, 1, v0
	v_cmp_ge_u32_e32 vcc, v3, v2
	v_add_u32_e32 v3, 1, v5
	s_nop 0
	v_cndmask_b32_e32 v0, v0, v4, vcc
	v_mul_lo_u32 v4, v2, v0
	v_add_u32_e32 v2, v4, v2
	v_cmp_ne_u32_e32 vcc, v3, v2
	s_and_saveexec_b64 s[6:7], vcc
	s_xor_b64 s[6:7], exec, s[6:7]
	s_cbranch_execz .LBB0_854
	s_waitcnt lgkmcnt(0)
	s_add_u32 s12, s22, 0x1e6c4500
	s_addc_u32 s13, s23, 0
	v_mov_b32_e32 v1, 0
	global_load_dword v1, v1, s[12:13] sc1
	s_waitcnt vmcnt(0)
	v_cmp_eq_u32_e32 vcc, v1, v0
	s_and_saveexec_b64 s[8:9], vcc
	s_cbranch_execz .LBB0_853
	s_add_u32 s10, s22, 0x1e6c1200
	s_addc_u32 s11, s23, 0
	s_mov_b32 s27, 1
	s_mov_b64 s[14:15], 0
	v_mov_b32_e32 v1, 0
	s_branch .LBB0_844

;   DI unsigned* bar() const { return (unsigned*)(ws + OFF_BAR); }
; __device__ __forceinline__ unsigned xb_ld(unsigned* p)              { return __hip_atomic_load(p, __ATOMIC_RELAXED, __HIP_MEMORY_SCOPE_AGENT); }
; __device__ __forceinline__ unsigned xb_add(unsigned* p, unsigned v) { return __hip_atomic_fetch_add(p, v, __ATOMIC_RELAXED, __HIP_MEMORY_SCOPE_AGENT); }
; #define XB_SPIN(cond, bar) do { unsigned _sp = 0; while (cond) { __builtin_amdgcn_s_sleep(1); \
;     if ((++_sp & 255u) == 0u) { if (xb_ld(&(bar)[XB_TMO])) break; if (_sp > XB_SPIN_CAP) { atomicAdd(&(bar)[XB_TMO], 1u); break; } } } } while (0)
; __device__ __forceinline__ void xcd_barrier(const XcdBarrier& b) {
;     ...
;     if (threadIdx.x == 0) {
;         unsigned* bar = b.bar;
;         __builtin_amdgcn_s_waitcnt(0);
;         unsigned nloc = b.st[0], nx = b.st[1];
;         if (nloc == 0u) { xcd_barrier_complete(bar, b.x, nloc, nx); b.st[0] = nloc; b.st[1] = nx; }
;         const unsigned old = xb_add(&bar[XB_XSUB(b.x)], 1u);
;         const unsigned gen = old / nloc;
;         if (old + 1u == (gen + 1u) * nloc) {
;             __builtin_amdgcn_fence(__ATOMIC_RELEASE, "agent");
;             asm volatile("s_waitcnt vmcnt(0)" ::: "memory");
;             const unsigned og = xb_add(&bar[XB_TOP], 1u);
;             const unsigned tg = og / nx;
;             if (og + 1u == (tg + 1u) * nx) xb_add(&bar[XB_TOPGEN], 1u);
;             else XB_SPIN(xb_ld(&bar[XB_TOPGEN]) == tg, bar);
;             __builtin_amdgcn_fence(__ATOMIC_ACQUIRE, "agent");
;             xb_add(&bar[XB_XGEN(b.x)], 1u);
;             asm volatile("s_waitcnt vmcnt(0)" ::: "memory");
;         } else {
;             XB_SPIN(xb_ld(&bar[XB_XGEN(b.x)]) == gen, bar);
;             __builtin_amdgcn_fence(__ATOMIC_ACQUIRE, "agent");
;             asm volatile("s_waitcnt vmcnt(0)" ::: "memory");
;         }
.LBB0_1673:
	s_or_b64 exec, exec, s[6:7]
	v_cvt_f32_u32_e32 v4, v2
	s_waitcnt vmcnt(0)
	v_readfirstlane_b32 s4, v3
	v_sub_u32_e32 v3, 0, v2
	v_rcp_iflag_f32_e32 v4, v4
	v_add_u32_e32 v5, s4, v0
	v_mul_f32_e32 v4, 0x4f7ffffe, v4
	v_cvt_u32_f32_e32 v4, v4
	v_mul_lo_u32 v0, v3, v4
	v_mul_hi_u32 v0, v4, v0
	v_add_u32_e32 v0, v4, v0
	v_mul_hi_u32 v0, v5, v0
	v_mul_lo_u32 v3, v0, v2
	v_sub_u32_e32 v3, v5, v3
	v_add_u32_e32 v4, 1, v0
	v_cmp_ge_u32_e32 vcc, v3, v2
	s_nop 1
	v_cndmask_b32_e32 v0, v0, v4, vcc
	v_sub_u32_e32 v4, v3, v2
	v_cndmask_b32_e32 v3, v3, v4, vcc
	v_add_u32_e32 v4, 1, v0
	v_cmp_ge_u32_e32 vcc, v3, v2
	v_add_u32_e32 v3, 1, v5
	s_nop 0
	v_cndmask_b32_e32 v0, v0, v4, vcc
	v_mul_lo_u32 v4, v2, v0
	v_add_u32_e32 v2, v4, v2
	v_cmp_ne_u32_e32 vcc, v3, v2
	s_and_saveexec_b64 s[4:5], vcc
	s_xor_b64 s[4:5], exec, s[4:5]
	s_cbranch_execz .LBB0_1687
	s_waitcnt lgkmcnt(0)
	s_add_u32 s10, s22, 0x1e6c4500
	s_addc_u32 s11, s23, 0
	v_mov_b32_e32 v1, 0
	global_load_dword v1, v1, s[10:11] sc1
	s_waitcnt vmcnt(0)
	v_cmp_eq_u32_e32 vcc, v1, v0
	s_and_saveexec_b64 s[6:7], vcc
	s_cbranch_execz .LBB0_1686
	s_add_u32 s8, s22, 0x1e6c1200
	s_addc_u32 s9, s23, 0
	s_mov_b32 s27, 1
	s_mov_b64 s[12:13], 0
	v_mov_b32_e32 v1, 0
	s_branch .LBB0_1677
